# diff attention: 5-slot LDS ring with loads staged 3 tiles ahead, workgroup barrier every second tile
# speedup vs baseline: 1.0065x; 1.0065x over previous
; #define LAS __attribute__((address_space(3)))
; template <int D1, int D2, int DV>
; DI void attn_core(f32x16 (&o)[DV / 32], float& l_out, LAS unsigned char* lds, const bf16_t* q1, const bf16_t* q2,
;                   const bf16_t* k1, long ldk1, const bf16_t* k2, long ldk2, const bf16_t* vt, long ldv, int ntiles) {
;     ...
;     gload(0); sstore(0); if (ntiles > 1) { gload(1); sstore(1); } __syncthreads();
;     for (int t = 0; t < ntiles; ++t) {
;         if (t + 2 < ntiles) gload(t + 2);
;         const LAS unsigned char* kb = lds + (t & 3) * BUF; const LAS unsigned char* vb = kb + KT;
;         f32x16 p[2];
;         {
;             bf16x8 kf[2][DQK / 16];
; #pragma unroll
;             for (int hf = 0; hf < 2; ++hf)
; #pragma unroll
;                 for (int d0 = 0; d0 < DQK / 16; ++d0) kf[hf][d0] = *(const LAS bf16x8*)(kb + (32 * hf + pr) * KROW + (16 * d0 + 8 * h) * 2);
;             __builtin_amdgcn_sched_barrier(0);
;             __builtin_amdgcn_s_setprio(2);
; #pragma unroll
;             for (int d0 = 0; d0 < DQK / 16; ++d0)
; #pragma unroll
;                 for (int hf = 0; hf < 2; ++hf) p[hf] = MFMA32(kf[hf][d0], qf[d0], d0 == 0 ? negm : p[hf]);
;             __builtin_amdgcn_sched_barrier(0);
;         }
;         constexpr int NBLK = DV / 32;
;         bf16x8 vk[2][NBLK];
;     ...
;         LDVK(0, 0);
;         __builtin_amdgcn_sched_barrier(0);
;         float ta = fmaxf(fmaxf(p[0][0], p[0][1]), p[1][0]), tb = fmaxf(fmaxf(p[0][2], p[0][3]), p[1][1]);
;         ta = fmaxf(fmaxf(ta, p[1][2]), p[1][3]);
; #pragma unroll
;         for (int i = 4; i < 16; i += 4) { ta = fmaxf(fmaxf(ta, p[0][i]), p[0][i + 1]); tb = fmaxf(fmaxf(tb, p[0][i + 2]), p[0][i + 3]); ta = fmaxf(fmaxf(ta, p[1][i]), p[1][i + 1]); tb = fmaxf(fmaxf(tb, p[1][i + 2]), p[1][i + 3]); }
;         float tm = fmaxf(ta, tb);
;         if (__any(t == 0 || tm > 8.0f)) {
;             tm = fmaxf(tm, __shfl_xor(tm, 32));
;             const float dl = (t == 0 || tm > 0.f) ? tm : 0.f; mrun += dl;
;             const float alpha = __builtin_amdgcn_exp2f(-dl); lrun *= alpha;
; #pragma unroll
;             for (int i = 0; i < 16; ++i) { p[0][i] -= dl; p[1][i] -= dl; negm[i] = -mrun; }
; #pragma unroll
;             for (int b = 0; b < DV / 32; ++b)
; #pragma unroll
;                 for (int i = 0; i < 16; ++i) o[b][i] *= alpha;
;         }
;         bf16x8 pf[4]; float rs = 0.f; u32x4 wq;
.LBB0_207:
	s_or_b64 exec, exec, s[0:1]
	v_mul_u32_u24_e32 v200, 0x90, v1
	v_add_f32_e32 v1, 0, v96
	v_add_f32_e32 v1, v97, v1
	v_add_f32_e32 v1, v98, v1
	v_add_f32_e32 v1, v99, v1
	v_add_f32_e32 v1, v100, v1
	v_add_f32_e32 v1, v101, v1
	v_add_f32_e32 v1, v102, v1
	v_add_f32_e32 v1, v103, v1
	v_add_f32_e32 v1, v104, v1
	v_add_f32_e32 v1, v105, v1
	v_add_f32_e32 v1, v106, v1
	v_add_f32_e32 v1, v107, v1
	v_add_f32_e32 v1, v108, v1
	v_add_f32_e32 v1, v109, v1
	v_add_f32_e32 v1, v110, v1
	v_add_f32_e32 v1, v111, v1
	v_add_f32_e32 v1, v3, v1
	v_add_f32_e32 v1, v4, v1
	v_add_f32_e32 v1, v5, v1
	v_add_f32_e32 v1, v6, v1
	v_add_f32_e32 v1, v7, v1
	v_add_f32_e32 v1, v8, v1
	v_add_f32_e32 v1, v9, v1
	v_add_f32_e32 v1, v10, v1
	v_add_f32_e32 v1, v11, v1
	v_mad_i64_i32 v[84:85], s[0:1], v151, s7, 0
	v_mad_i64_i32 v[86:87], s[0:1], v152, s7, 0
	v_add_f32_e32 v1, v12, v1
	v_add_f32_e32 v1, v13, v1
	s_lshl_b32 s0, s4, 7
	v_add_f32_e32 v1, v14, v1
	s_and_b32 s0, s0, 0x200
	s_lshl_b32 s1, s6, 7
	v_add_f32_e32 v1, v15, v1
	s_add_i32 s0, s0, s1
	v_add_f32_e32 v1, v80, v1
	s_bfe_u32 s7, s0, 0x30007
	v_add_f32_e32 v1, v81, v1
	s_lshl_b32 s6, s7, 8
	v_add_f32_e32 v1, v82, v1
	s_add_u32 s0, s6, s28
	v_add_f32_e32 v201, v2, v1
	v_lshlrev_b64 v[2:3], 12, v[146:147]
	s_addc_u32 s1, 0, s29
	v_lshl_add_u64 v[2:3], s[0:1], 0, v[2:3]
	v_readlane_b32 s0, v243, 52
	v_lshl_add_u64 v[2:3], v[148:149], 1, v[2:3]
	v_readlane_b32 s1, v243, 53
	s_waitcnt vmcnt(1)
	ds_write_b128 v145, v[132:135] offset:64512
	s_waitcnt vmcnt(0)
	ds_write_b128 v150, v[136:139] offset:64512
	v_lshl_add_u64 v[162:163], s[0:1], 0, v[2:3]
	v_mad_u64_u32 v[2:3], s[0:1], s7, v187, v[84:85]
	v_mov_b32_e32 v145, v157
	s_add_u32 s0, s10, s42
	v_readlane_b32 s1, v243, 59
	v_lshl_add_u64 v[2:3], v[2:3], 0, v[144:145]
	s_addc_u32 s1, s1, s43
	v_lshl_add_u64 v[164:165], s[0:1], 0, v[2:3]
	v_mad_u64_u32 v[2:3], s[8:9], s7, v187, v[86:87]
	v_lshl_add_u64 v[2:3], v[2:3], 0, v[144:145]
	s_mul_i32 s44, s7, 0x840000
	s_mov_b32 s45, s24
	v_lshl_add_u64 v[166:167], s[0:1], 0, v[2:3]
	s_mov_b32 s7, 3
	v_mov_b32_e32 v1, v0
	v_mov_b32_e32 v2, v0
	v_mov_b32_e32 v3, v0
	v_mov_b32_e32 v4, v0
	v_mov_b32_e32 v5, v0
	v_mov_b32_e32 v6, v0
	v_mov_b32_e32 v7, v0
	v_mov_b32_e32 v8, v0
	v_mov_b32_e32 v9, v0
	v_mov_b32_e32 v10, v0
	v_mov_b32_e32 v11, v0
	v_mov_b32_e32 v12, v0
	v_mov_b32_e32 v13, v0
	v_mov_b32_e32 v14, v0
	v_mov_b32_e32 v15, v0
	global_load_dwordx4 v[128:131], v[162:163], off
	global_load_dwordx4 v[132:135], v[164:165], off
	global_load_dwordx4 v[136:139], v[166:167], off
	s_mov_b64 s[0:1], 0x40000
	v_lshl_add_u64 v[162:163], v[162:163], 0, s[0:1]
	s_mov_b64 s[0:1], 0x80
	v_lshl_add_u64 v[164:165], v[164:165], 0, s[0:1]
	v_lshl_add_u64 v[166:167], v[166:167], 0, s[0:1]
	s_waitcnt lgkmcnt(0)
	s_mov_b32 s7, 1
	s_movk_i32 s9, 0x6c00
	v_add3_u32 v247, s9, v200, v197
	ds_read_b128 v[140:143], v247 offset:0
	ds_read_b128 v[144:147], v247 offset:32
	ds_read_b128 v[148:151], v247 offset:64
	ds_read_b128 v[152:155], v247 offset:96
	v_add3_u32 v246, s9, v199, v197
	s_waitcnt lgkmcnt(3)
	v_mfma_f32_32x32x16_bf16 v[96:111], v[140:143], v[112:115], v[0:15]
	ds_read_b128 v[140:143], v247 offset:4608
	s_waitcnt lgkmcnt(3)
	v_mfma_f32_32x32x16_bf16 v[96:111], v[144:147], v[116:119], v[96:111]
	ds_read_b128 v[144:147], v247 offset:4640
	s_waitcnt lgkmcnt(3)
	v_mfma_f32_32x32x16_bf16 v[96:111], v[148:151], v[120:123], v[96:111]
	ds_read_b128 v[148:151], v247 offset:4672
	s_waitcnt lgkmcnt(3)
	v_mfma_f32_32x32x16_bf16 v[96:111], v[152:155], v[124:127], v[96:111]
	ds_read_b128 v[152:155], v247 offset:4704
	s_waitcnt lgkmcnt(3)
	v_mfma_f32_32x32x16_bf16 v[80:95], v[140:143], v[112:115], v[0:15]
	ds_read_b128 v[208:211], v246 offset:9216
	s_waitcnt lgkmcnt(3)
	v_mfma_f32_32x32x16_bf16 v[80:95], v[144:147], v[116:119], v[80:95]
	ds_read_b128 v[212:215], v246 offset:13824
	s_waitcnt lgkmcnt(3)
	v_mfma_f32_32x32x16_bf16 v[80:95], v[148:151], v[120:123], v[80:95]
	ds_read_b128 v[216:219], v246 offset:18432
	s_waitcnt lgkmcnt(3)
	v_mfma_f32_32x32x16_bf16 v[80:95], v[152:155], v[124:127], v[80:95]
	ds_read_b128 v[220:223], v246 offset:23040
	s_nop 15
	v_exp_f32_e32 v232, v96
	v_exp_f32_e32 v233, v97
	s_nop 0
	v_cvt_pk_bf16_f32 v224, v232, v233
	v_exp_f32_e32 v234, v98
	v_exp_f32_e32 v235, v99
	s_nop 0
	v_cvt_pk_bf16_f32 v225, v234, v235
	v_exp_f32_e32 v236, v100
	v_exp_f32_e32 v237, v101
	s_nop 0
	v_cvt_pk_bf16_f32 v226, v236, v237
	v_exp_f32_e32 v238, v102
	v_exp_f32_e32 v239, v103
	s_nop 0
	v_cvt_pk_bf16_f32 v227, v238, v239
	s_mov_b32 s26, 0x14400
	s_waitcnt vmcnt(0)
	v_add3_u32 v247, s26, v195, v196
	ds_write_b128 v247, v[128:131] offset:0
	v_add3_u32 v247, s26, v193, v156
	ds_write_b128 v247, v[132:135] offset:9216
	v_add3_u32 v247, s26, v194, v156
	ds_write_b128 v247, v[136:139] offset:9216
	s_mov_b32 s8, 0x6c00
	s_mov_b32 s9, 0xd800
	s_mov_b32 s26, 0x1b000
	s_nop 1
.Lda1_top:
	v_add3_u32 v246, s8, v199, v197
	s_cmpk_lt_u32 s7, 129
	s_cbranch_scc0 .Lda1_nog
	global_load_dwordx4 v[128:131], v[162:163], off
	global_load_dwordx4 v[132:135], v[164:165], off
	global_load_dwordx4 v[136:139], v[166:167], off
	s_mov_b64 s[0:1], 0x40000
	v_lshl_add_u64 v[162:163], v[162:163], 0, s[0:1]
	s_mov_b64 s[0:1], 0x80
	v_lshl_add_u64 v[164:165], v[164:165], 0, s[0:1]
	v_lshl_add_u64 v[166:167], v[166:167], 0, s[0:1]
; template <int D1, int D2, int DV>
; DI void attn_core(f32x16 (&o)[DV / 32], float& l_out, LAS unsigned char* lds, const bf16_t* q1, const bf16_t* q2,
;                   const bf16_t* k1, long ldk1, const bf16_t* k2, long ldk2, const bf16_t* vt, long ldv, int ntiles) {
;     ...
;     for (int t = 0; t < ntiles; ++t) {
;         if (t + 2 < ntiles) gload(t + 2);
;         const LAS unsigned char* kb = lds + (t & 3) * BUF; const LAS unsigned char* vb = kb + KT;
;         f32x16 p[2];
;         {
;             bf16x8 kf[2][DQK / 16];
; #pragma unroll
;             for (int hf = 0; hf < 2; ++hf)
; #pragma unroll
;                 for (int d0 = 0; d0 < DQK / 16; ++d0) kf[hf][d0] = *(const LAS bf16x8*)(kb + (32 * hf + pr) * KROW + (16 * d0 + 8 * h) * 2);
;             __builtin_amdgcn_sched_barrier(0);
;             __builtin_amdgcn_s_setprio(2);
; #pragma unroll
;             for (int d0 = 0; d0 < DQK / 16; ++d0)
; #pragma unroll
;                 for (int hf = 0; hf < 2; ++hf) p[hf] = MFMA32(kf[hf][d0], qf[d0], d0 == 0 ? negm : p[hf]);
;             __builtin_amdgcn_sched_barrier(0);
;         }
;         constexpr int NBLK = DV / 32;
;         bf16x8 vk[2][NBLK];
;     ...
;         LDVK(0, 0);
;         __builtin_amdgcn_sched_barrier(0);
;         float ta = fmaxf(fmaxf(p[0][0], p[0][1]), p[1][0]), tb = fmaxf(fmaxf(p[0][2], p[0][3]), p[1][1]);
;         ta = fmaxf(fmaxf(ta, p[1][2]), p[1][3]);
; #pragma unroll
;         for (int i = 4; i < 16; i += 4) { ta = fmaxf(fmaxf(ta, p[0][i]), p[0][i + 1]); tb = fmaxf(fmaxf(tb, p[0][i + 2]), p[0][i + 3]); ta = fmaxf(fmaxf(ta, p[1][i]), p[1][i + 1]); tb = fmaxf(fmaxf(tb, p[1][i + 2]), p[1][i + 3]); }
;         float tm = fmaxf(ta, tb);
;         if (__any(t == 0 || tm > 8.0f)) {
;             tm = fmaxf(tm, __shfl_xor(tm, 32));
;             const float dl = (t == 0 || tm > 0.f) ? tm : 0.f; mrun += dl;
;             const float alpha = __builtin_amdgcn_exp2f(-dl); lrun *= alpha;
; #pragma unroll
;             for (int i = 0; i < 16; ++i) { p[0][i] -= dl; p[1][i] -= dl; negm[i] = -mrun; }
; #pragma unroll
;             for (int b = 0; b < DV / 32; ++b)
; #pragma unroll
;                 for (int i = 0; i < 16; ++i) o[b][i] *= alpha;
;         }
;         bf16x8 pf[4]; float rs = 0.f; u32x4 wq;
;     ...
;         EXPPART(0, 0); EXPPART(0, 1); EXPPART(0, 2); EXPPART(0, 3); pf[0] = __builtin_bit_cast(bf16x8, wq);
.Lda1_nog:
	s_waitcnt lgkmcnt(3)
	v_mfma_f32_32x32x16_bf16 v[64:79], v[208:211], v[224:227], v[64:79]
	v_exp_f32_e32 v104, v104
	ds_read_b128 v[208:211], v246 offset:9248
	v_exp_f32_e32 v105, v105
	s_nop 0
	v_cvt_pk_bf16_f32 v228, v104, v105
	s_waitcnt lgkmcnt(3)
	v_mfma_f32_32x32x16_bf16 v[48:63], v[212:215], v[224:227], v[48:63]
	v_exp_f32_e32 v106, v106
	ds_read_b128 v[212:215], v246 offset:13856
	v_exp_f32_e32 v107, v107
	s_nop 0
	v_cvt_pk_bf16_f32 v229, v106, v107
	s_waitcnt lgkmcnt(3)
	v_mfma_f32_32x32x16_bf16 v[32:47], v[216:219], v[224:227], v[32:47]
	v_exp_f32_e32 v108, v108
	ds_read_b128 v[216:219], v246 offset:18464
	v_exp_f32_e32 v109, v109
	s_nop 0
	v_cvt_pk_bf16_f32 v230, v108, v109
	s_waitcnt lgkmcnt(3)
	v_mfma_f32_32x32x16_bf16 v[16:31], v[220:223], v[224:227], v[16:31]
	v_exp_f32_e32 v110, v110
	ds_read_b128 v[220:223], v246 offset:23072
	v_exp_f32_e32 v111, v111
	s_nop 0
	v_cvt_pk_bf16_f32 v231, v110, v111
	s_bitcmp1_b32 s7, 0
	s_cbranch_scc0 .Lda1_nobar
	s_barrier
.Lda1_nobar:
	v_add3_u32 v247, s9, v200, v197
	ds_read_b128 v[140:143], v247 offset:0
	ds_read_b128 v[144:147], v247 offset:32
	ds_read_b128 v[148:151], v247 offset:64
	ds_read_b128 v[152:155], v247 offset:96
	s_waitcnt lgkmcnt(7)
	v_mfma_f32_32x32x16_bf16 v[64:79], v[208:211], v[228:231], v[64:79]
	v_exp_f32_e32 v80, v80
	ds_read_b128 v[208:211], v246 offset:9280
	v_exp_f32_e32 v81, v81
	v_add_f32_e32 v202, v104, v105
	v_cvt_pk_bf16_f32 v224, v80, v81
	s_waitcnt lgkmcnt(7)
	v_mfma_f32_32x32x16_bf16 v[48:63], v[212:215], v[228:231], v[48:63]
	v_exp_f32_e32 v82, v82
	ds_read_b128 v[212:215], v246 offset:13888
	v_add_f32_e32 v202, v106, v202
	v_exp_f32_e32 v83, v83
	v_add_f32_e32 v202, v107, v202
	v_cvt_pk_bf16_f32 v225, v82, v83
	s_waitcnt lgkmcnt(7)
	v_mfma_f32_32x32x16_bf16 v[32:47], v[216:219], v[228:231], v[32:47]
	v_exp_f32_e32 v84, v84
	ds_read_b128 v[216:219], v246 offset:18496
	v_add_f32_e32 v202, v108, v202
	v_exp_f32_e32 v85, v85
	v_add_f32_e32 v202, v109, v202
	v_cvt_pk_bf16_f32 v226, v84, v85
	s_waitcnt lgkmcnt(7)
	v_mfma_f32_32x32x16_bf16 v[16:31], v[220:223], v[228:231], v[16:31]
	v_exp_f32_e32 v86, v86
	ds_read_b128 v[220:223], v246 offset:23104
	v_add_f32_e32 v202, v110, v202
	v_exp_f32_e32 v87, v87
	v_add_f32_e32 v202, v111, v202
	v_cvt_pk_bf16_f32 v227, v86, v87
	s_waitcnt lgkmcnt(7)
	v_mfma_f32_32x32x16_bf16 v[96:111], v[140:143], v[112:115], v[0:15]
	v_exp_f32_e32 v88, v88
	ds_read_b128 v[140:143], v247 offset:4608
	v_exp_f32_e32 v89, v89
	s_nop 0
	v_cvt_pk_bf16_f32 v228, v88, v89
	s_waitcnt lgkmcnt(7)
	v_mfma_f32_32x32x16_bf16 v[96:111], v[144:147], v[116:119], v[96:111]
	v_exp_f32_e32 v90, v90
	ds_read_b128 v[144:147], v247 offset:4640
	v_exp_f32_e32 v91, v91
	s_nop 0
	v_cvt_pk_bf16_f32 v229, v90, v91
	s_waitcnt lgkmcnt(7)
	v_mfma_f32_32x32x16_bf16 v[96:111], v[148:151], v[120:123], v[96:111]
	v_exp_f32_e32 v92, v92
	ds_read_b128 v[148:151], v247 offset:4672
	v_exp_f32_e32 v93, v93
	s_nop 0
	v_cvt_pk_bf16_f32 v230, v92, v93
	s_waitcnt lgkmcnt(7)
	v_mfma_f32_32x32x16_bf16 v[96:111], v[152:155], v[124:127], v[96:111]
	v_exp_f32_e32 v94, v94
	ds_read_b128 v[152:155], v247 offset:4704
	v_exp_f32_e32 v95, v95
	s_nop 0
	v_cvt_pk_bf16_f32 v231, v94, v95
	s_waitcnt lgkmcnt(7)
	v_mfma_f32_32x32x16_bf16 v[64:79], v[208:211], v[224:227], v[64:79]
	v_add_f32_e32 v202, v88, v202
	ds_read_b128 v[208:211], v246 offset:9312
	v_add_f32_e32 v203, v232, v233
	v_add_f32_e32 v202, v89, v202
	v_add_f32_e32 v203, v80, v203
	v_add_f32_e32 v202, v81, v202
	s_waitcnt lgkmcnt(7)
	v_mfma_f32_32x32x16_bf16 v[48:63], v[212:215], v[224:227], v[48:63]
	v_add_f32_e32 v202, v90, v202
	ds_read_b128 v[212:215], v246 offset:13920
	v_add_f32_e32 v203, v234, v203
	v_add_f32_e32 v202, v91, v202
	v_add_f32_e32 v203, v235, v203
	v_add_f32_e32 v202, v82, v202
	v_add_f32_e32 v203, v83, v203
	s_waitcnt lgkmcnt(7)
	v_mfma_f32_32x32x16_bf16 v[32:47], v[216:219], v[224:227], v[32:47]
	v_add_f32_e32 v202, v92, v202
	ds_read_b128 v[216:219], v246 offset:18528
	v_add_f32_e32 v203, v236, v203
	v_add_f32_e32 v202, v93, v202
	v_add_f32_e32 v203, v237, v203
	v_add_f32_e32 v202, v84, v202
	v_add_f32_e32 v203, v85, v203
	s_waitcnt lgkmcnt(7)
	v_mfma_f32_32x32x16_bf16 v[16:31], v[220:223], v[224:227], v[16:31]
	v_add_f32_e32 v202, v94, v202
	ds_read_b128 v[220:223], v246 offset:23136
	v_add_f32_e32 v203, v238, v203
	v_add_f32_e32 v202, v95, v202
	v_add_f32_e32 v203, v239, v203
	v_add_f32_e32 v202, v86, v202
	v_add_f32_e32 v203, v87, v203
	v_add_f32_e32 v202, v203, v202
	v_add_f32_e32 v201, v202, v201
	s_waitcnt lgkmcnt(7)
	v_mfma_f32_32x32x16_bf16 v[80:95], v[140:143], v[112:115], v[0:15]
	s_waitcnt vmcnt(0)
	v_exp_f32_e32 v232, v96
	v_exp_f32_e32 v233, v97
	v_add3_u32 v247, s26, v195, v196
	v_cvt_pk_bf16_f32 v224, v232, v233
	ds_write_b128 v247, v[128:131] offset:0
	s_waitcnt lgkmcnt(7)
	v_mfma_f32_32x32x16_bf16 v[80:95], v[144:147], v[116:119], v[80:95]
	v_exp_f32_e32 v234, v98
	v_exp_f32_e32 v235, v99
	v_add3_u32 v247, s26, v193, v156
	v_cvt_pk_bf16_f32 v225, v234, v235
	ds_write_b128 v247, v[132:135] offset:9216
	s_waitcnt lgkmcnt(7)
	v_mfma_f32_32x32x16_bf16 v[80:95], v[148:151], v[120:123], v[80:95]
	v_exp_f32_e32 v236, v100
	v_exp_f32_e32 v237, v101
	v_add3_u32 v247, s26, v194, v156
	v_cvt_pk_bf16_f32 v226, v236, v237
	ds_write_b128 v247, v[136:139] offset:9216
	s_waitcnt lgkmcnt(7)
	v_mfma_f32_32x32x16_bf16 v[80:95], v[152:155], v[124:127], v[80:95]
	v_exp_f32_e32 v238, v102
	v_exp_f32_e32 v239, v103
	v_add3_u32 v246, s9, v199, v197
	v_cvt_pk_bf16_f32 v227, v238, v239
	s_waitcnt lgkmcnt(6)
	v_mfma_f32_32x32x16_bf16 v[64:79], v[208:211], v[228:231], v[64:79]
	ds_read_b128 v[208:211], v246 offset:9216
	s_waitcnt lgkmcnt(6)
	v_mfma_f32_32x32x16_bf16 v[48:63], v[212:215], v[228:231], v[48:63]
	ds_read_b128 v[212:215], v246 offset:13824
	s_waitcnt lgkmcnt(6)
	v_mfma_f32_32x32x16_bf16 v[32:47], v[216:219], v[228:231], v[32:47]
	ds_read_b128 v[216:219], v246 offset:18432
	s_waitcnt lgkmcnt(6)
	v_mfma_f32_32x32x16_bf16 v[16:31], v[220:223], v[228:231], v[16:31]
	ds_read_b128 v[220:223], v246 offset:23040
	v_cmp_lt_f32_e32 vcc, 0x46800000, v202
	s_add_i32 s8, s8, 0x6c00
	s_cmp_eq_u32 s8, 0x21c00
	s_cselect_b32 s8, 0, s8
	s_add_i32 s9, s9, 0x6c00
	s_cmp_eq_u32 s9, 0x21c00
	s_cselect_b32 s9, 0, s9
	s_add_i32 s26, s26, 0x6c00
	s_cmp_eq_u32 s26, 0x21c00
	s_cselect_b32 s26, 0, s26
	s_add_i32 s7, s7, 1
	s_cmpk_eq_u32 s7, 132
	s_cbranch_scc1 .Lda1_exit
	s_cbranch_vccnz .Lda1_rare_l
	s_branch .Lda1_top

; #define LAS __attribute__((address_space(3)))
; template <int D1, int D2, int DV>
; DI void attn_core(f32x16 (&o)[DV / 32], float& l_out, LAS unsigned char* lds, const bf16_t* q1, const bf16_t* q2,
;                   const bf16_t* k1, long ldk1, const bf16_t* k2, long ldk2, const bf16_t* vt, long ldv, int ntiles) {
;     ...
;     gload(0); sstore(0); if (ntiles > 1) { gload(1); sstore(1); } __syncthreads();
;     for (int t = 0; t < ntiles; ++t) {
;         if (t + 2 < ntiles) gload(t + 2);
;         const LAS unsigned char* kb = lds + (t & 3) * BUF; const LAS unsigned char* vb = kb + KT;
;         f32x16 p[2];
;         {
;             bf16x8 kf[2][DQK / 16];
; #pragma unroll
;             for (int hf = 0; hf < 2; ++hf)
; #pragma unroll
;                 for (int d0 = 0; d0 < DQK / 16; ++d0) kf[hf][d0] = *(const LAS bf16x8*)(kb + (32 * hf + pr) * KROW + (16 * d0 + 8 * h) * 2);
;             __builtin_amdgcn_sched_barrier(0);
;             __builtin_amdgcn_s_setprio(2);
; #pragma unroll
;             for (int d0 = 0; d0 < DQK / 16; ++d0)
; #pragma unroll
;                 for (int hf = 0; hf < 2; ++hf) p[hf] = MFMA32(kf[hf][d0], qf[d0], d0 == 0 ? negm : p[hf]);
;             __builtin_amdgcn_sched_barrier(0);
;         }
;         constexpr int NBLK = DV / 32;
;         bf16x8 vk[2][NBLK];
;     ...
;         LDVK(0, 0);
;         __builtin_amdgcn_sched_barrier(0);
;         float ta = fmaxf(fmaxf(p[0][0], p[0][1]), p[1][0]), tb = fmaxf(fmaxf(p[0][2], p[0][3]), p[1][1]);
;         ta = fmaxf(fmaxf(ta, p[1][2]), p[1][3]);
; #pragma unroll
;         for (int i = 4; i < 16; i += 4) { ta = fmaxf(fmaxf(ta, p[0][i]), p[0][i + 1]); tb = fmaxf(fmaxf(tb, p[0][i + 2]), p[0][i + 3]); ta = fmaxf(fmaxf(ta, p[1][i]), p[1][i + 1]); tb = fmaxf(fmaxf(tb, p[1][i + 2]), p[1][i + 3]); }
;         float tm = fmaxf(ta, tb);
;         if (__any(t == 0 || tm > 8.0f)) {
;             tm = fmaxf(tm, __shfl_xor(tm, 32));
;             const float dl = (t == 0 || tm > 0.f) ? tm : 0.f; mrun += dl;
;             const float alpha = __builtin_amdgcn_exp2f(-dl); lrun *= alpha;
; #pragma unroll
;             for (int i = 0; i < 16; ++i) { p[0][i] -= dl; p[1][i] -= dl; negm[i] = -mrun; }
; #pragma unroll
;             for (int b = 0; b < DV / 32; ++b)
; #pragma unroll
;                 for (int i = 0; i < 16; ++i) o[b][i] *= alpha;
;         }
;         bf16x8 pf[4]; float rs = 0.f; u32x4 wq;
.LBB0_238:
	s_or_b64 exec, exec, s[0:1]
	v_add_f32_e32 v83, 0, v111
	v_add_f32_e32 v83, v140, v83
	v_add_f32_e32 v83, v141, v83
	v_add_f32_e32 v83, v142, v83
	v_add_f32_e32 v83, v143, v83
	v_add_f32_e32 v83, v144, v83
	v_add_f32_e32 v83, v145, v83
	v_add_f32_e32 v83, v146, v83
	v_add_f32_e32 v83, v147, v83
	v_add_f32_e32 v83, v148, v83
	v_add_f32_e32 v83, v149, v83
	v_add_f32_e32 v83, v150, v83
	v_add_f32_e32 v83, v151, v83
	v_add_f32_e32 v83, v152, v83
	v_add_f32_e32 v83, v153, v83
	v_add_f32_e32 v83, v154, v83
	v_add_f32_e32 v66, v66, v83
	v_add_f32_e32 v66, v67, v66
	v_add_f32_e32 v66, v68, v66
	v_add_f32_e32 v66, v69, v66
	v_add_f32_e32 v66, v70, v66
	v_add_f32_e32 v66, v71, v66
	v_add_f32_e32 v66, v72, v66
	v_add_f32_e32 v66, v73, v66
	v_add_f32_e32 v66, v74, v66
	v_add_f32_e32 v66, v75, v66
	v_add_f32_e32 v66, v76, v66
	v_add_f32_e32 v66, v77, v66
	v_add_f32_e32 v66, v78, v66
	v_add_f32_e32 v66, v79, v66
	v_mad_i64_i32 v[84:85], s[0:1], v108, s7, 0
	v_mad_i64_i32 v[86:87], s[0:1], v109, s7, 0
	v_add_f32_e32 v66, v80, v66
	v_add_f32_e32 v66, v81, v66
	s_add_u32 s0, s6, s28
	v_add_f32_e32 v199, v82, v66
	v_lshlrev_b64 v[66:67], 12, v[104:105]
	s_addc_u32 s1, 0, s29
	v_lshl_add_u64 v[66:67], s[0:1], 0, v[66:67]
	v_readlane_b32 s0, v243, 60
	v_lshl_add_u64 v[66:67], v[106:107], 1, v[66:67]
	v_readlane_b32 s1, v243, 61
	s_waitcnt vmcnt(1)
	ds_write_b128 v65, v[132:135] offset:64512
	s_waitcnt vmcnt(0)
	ds_write_b128 v103, v[136:139] offset:64512
	v_lshl_add_u64 v[160:161], s[0:1], 0, v[66:67]
	v_lshl_add_u64 v[66:67], s[44:45], 0, v[84:85]
	v_mov_b32_e32 v103, v157
	s_add_u32 s0, s10, s42
	v_readlane_b32 s1, v243, 59
	v_lshl_add_u64 v[66:67], v[66:67], 0, v[102:103]
	s_addc_u32 s1, s1, s43
	v_lshl_add_u64 v[162:163], s[0:1], 0, v[66:67]
	v_lshl_add_u64 v[66:67], s[44:45], 0, v[86:87]
	v_lshl_add_u64 v[66:67], v[66:67], 0, v[102:103]
	v_mul_u32_u24_e32 v198, 0x90, v110
	v_lshl_add_u64 v[164:165], s[0:1], 0, v[66:67]
	s_mov_b32 s6, 3
	v_mov_b32_e32 v65, v64
	v_mov_b32_e32 v66, v64
	v_mov_b32_e32 v67, v64
	v_mov_b32_e32 v68, v64
	v_mov_b32_e32 v69, v64
	v_mov_b32_e32 v70, v64
	v_mov_b32_e32 v71, v64
	v_mov_b32_e32 v72, v64
	v_mov_b32_e32 v73, v64
	v_mov_b32_e32 v74, v64
	v_mov_b32_e32 v75, v64
	v_mov_b32_e32 v76, v64
	v_mov_b32_e32 v77, v64
	v_mov_b32_e32 v78, v64
	v_mov_b32_e32 v79, v64
	global_load_dwordx4 v[128:131], v[160:161], off
	global_load_dwordx4 v[132:135], v[162:163], off
	global_load_dwordx4 v[136:139], v[164:165], off
	s_mov_b64 s[0:1], 0x40000
	v_lshl_add_u64 v[160:161], v[160:161], 0, s[0:1]
	s_mov_b64 s[0:1], 0x80
	v_lshl_add_u64 v[162:163], v[162:163], 0, s[0:1]
	v_lshl_add_u64 v[164:165], v[164:165], 0, s[0:1]
	s_waitcnt lgkmcnt(0)
	s_mov_b32 s7, 1
	s_movk_i32 s9, 0x6c00
	v_add3_u32 v247, s9, v198, v195
	ds_read_b128 v[140:143], v247 offset:0
	ds_read_b128 v[144:147], v247 offset:32
	ds_read_b128 v[148:151], v247 offset:64
	ds_read_b128 v[152:155], v247 offset:96
	v_add3_u32 v246, s9, v197, v195
	s_waitcnt lgkmcnt(3)
	v_mfma_f32_32x32x16_bf16 v[96:111], v[140:143], v[112:115], v[64:79]
	ds_read_b128 v[140:143], v247 offset:4608
	s_waitcnt lgkmcnt(3)
	v_mfma_f32_32x32x16_bf16 v[96:111], v[144:147], v[116:119], v[96:111]
	ds_read_b128 v[144:147], v247 offset:4640
	s_waitcnt lgkmcnt(3)
	v_mfma_f32_32x32x16_bf16 v[96:111], v[148:151], v[120:123], v[96:111]
	ds_read_b128 v[148:151], v247 offset:4672
	s_waitcnt lgkmcnt(3)
	v_mfma_f32_32x32x16_bf16 v[96:111], v[152:155], v[124:127], v[96:111]
	ds_read_b128 v[152:155], v247 offset:4704
	s_waitcnt lgkmcnt(3)
	v_mfma_f32_32x32x16_bf16 v[80:95], v[140:143], v[112:115], v[64:79]
	ds_read_b128 v[208:211], v246 offset:9216
	s_waitcnt lgkmcnt(3)
	v_mfma_f32_32x32x16_bf16 v[80:95], v[144:147], v[116:119], v[80:95]
	ds_read_b128 v[212:215], v246 offset:13824
	s_waitcnt lgkmcnt(3)
	v_mfma_f32_32x32x16_bf16 v[80:95], v[148:151], v[120:123], v[80:95]
	ds_read_b128 v[216:219], v246 offset:18432
	s_waitcnt lgkmcnt(3)
	v_mfma_f32_32x32x16_bf16 v[80:95], v[152:155], v[124:127], v[80:95]
	ds_read_b128 v[220:223], v246 offset:23040
	s_nop 15
	v_exp_f32_e32 v232, v96
	v_exp_f32_e32 v233, v97
	s_nop 0
	v_cvt_pk_bf16_f32 v224, v232, v233
	v_exp_f32_e32 v234, v98
	v_exp_f32_e32 v235, v99
	s_nop 0
	v_cvt_pk_bf16_f32 v225, v234, v235
	v_exp_f32_e32 v236, v100
	v_exp_f32_e32 v237, v101
	s_nop 0
	v_cvt_pk_bf16_f32 v226, v236, v237
	v_exp_f32_e32 v238, v102
	v_exp_f32_e32 v239, v103
	s_nop 0
	v_cvt_pk_bf16_f32 v227, v238, v239
	s_mov_b32 s26, 0x14400
	s_waitcnt vmcnt(0)
	v_add3_u32 v247, s26, v193, v194
	ds_write_b128 v247, v[128:131] offset:0
	v_add3_u32 v247, s26, v167, v156
	ds_write_b128 v247, v[132:135] offset:9216
	v_add3_u32 v247, s26, v192, v156
	ds_write_b128 v247, v[136:139] offset:9216
	s_mov_b32 s8, 0x6c00
	s_mov_b32 s9, 0xd800
	s_mov_b32 s26, 0x1b000
	s_nop 1
.Lda2_top:
	v_add3_u32 v246, s8, v197, v195
	s_cmpk_lt_u32 s7, 129
	s_cbranch_scc0 .Lda2_nog
	global_load_dwordx4 v[128:131], v[160:161], off
	global_load_dwordx4 v[132:135], v[162:163], off
	global_load_dwordx4 v[136:139], v[164:165], off
	s_mov_b64 s[0:1], 0x40000
	v_lshl_add_u64 v[160:161], v[160:161], 0, s[0:1]
	s_mov_b64 s[0:1], 0x80
	v_lshl_add_u64 v[162:163], v[162:163], 0, s[0:1]
	v_lshl_add_u64 v[164:165], v[164:165], 0, s[0:1]
; template <int D1, int D2, int DV>
; DI void attn_core(f32x16 (&o)[DV / 32], float& l_out, LAS unsigned char* lds, const bf16_t* q1, const bf16_t* q2,
;                   const bf16_t* k1, long ldk1, const bf16_t* k2, long ldk2, const bf16_t* vt, long ldv, int ntiles) {
;     ...
;     for (int t = 0; t < ntiles; ++t) {
;         if (t + 2 < ntiles) gload(t + 2);
;         const LAS unsigned char* kb = lds + (t & 3) * BUF; const LAS unsigned char* vb = kb + KT;
;         f32x16 p[2];
;         {
;             bf16x8 kf[2][DQK / 16];
; #pragma unroll
;             for (int hf = 0; hf < 2; ++hf)
; #pragma unroll
;                 for (int d0 = 0; d0 < DQK / 16; ++d0) kf[hf][d0] = *(const LAS bf16x8*)(kb + (32 * hf + pr) * KROW + (16 * d0 + 8 * h) * 2);
;             __builtin_amdgcn_sched_barrier(0);
;             __builtin_amdgcn_s_setprio(2);
; #pragma unroll
;             for (int d0 = 0; d0 < DQK / 16; ++d0)
; #pragma unroll
;                 for (int hf = 0; hf < 2; ++hf) p[hf] = MFMA32(kf[hf][d0], qf[d0], d0 == 0 ? negm : p[hf]);
;             __builtin_amdgcn_sched_barrier(0);
;         }
;         constexpr int NBLK = DV / 32;
;         bf16x8 vk[2][NBLK];
;     ...
;         LDVK(0, 0);
;         __builtin_amdgcn_sched_barrier(0);
;         float ta = fmaxf(fmaxf(p[0][0], p[0][1]), p[1][0]), tb = fmaxf(fmaxf(p[0][2], p[0][3]), p[1][1]);
;         ta = fmaxf(fmaxf(ta, p[1][2]), p[1][3]);
; #pragma unroll
;         for (int i = 4; i < 16; i += 4) { ta = fmaxf(fmaxf(ta, p[0][i]), p[0][i + 1]); tb = fmaxf(fmaxf(tb, p[0][i + 2]), p[0][i + 3]); ta = fmaxf(fmaxf(ta, p[1][i]), p[1][i + 1]); tb = fmaxf(fmaxf(tb, p[1][i + 2]), p[1][i + 3]); }
;         float tm = fmaxf(ta, tb);
;         if (__any(t == 0 || tm > 8.0f)) {
;             tm = fmaxf(tm, __shfl_xor(tm, 32));
;             const float dl = (t == 0 || tm > 0.f) ? tm : 0.f; mrun += dl;
;             const float alpha = __builtin_amdgcn_exp2f(-dl); lrun *= alpha;
; #pragma unroll
;             for (int i = 0; i < 16; ++i) { p[0][i] -= dl; p[1][i] -= dl; negm[i] = -mrun; }
; #pragma unroll
;             for (int b = 0; b < DV / 32; ++b)
; #pragma unroll
;                 for (int i = 0; i < 16; ++i) o[b][i] *= alpha;
;         }
;         bf16x8 pf[4]; float rs = 0.f; u32x4 wq;
;     ...
;         EXPPART(0, 0); EXPPART(0, 1); EXPPART(0, 2); EXPPART(0, 3); pf[0] = __builtin_bit_cast(bf16x8, wq);
.Lda2_nog:
	s_waitcnt lgkmcnt(3)
	v_mfma_f32_32x32x16_bf16 v[0:15], v[208:211], v[224:227], v[0:15]
	v_exp_f32_e32 v104, v104
	ds_read_b128 v[208:211], v246 offset:9248
	v_exp_f32_e32 v105, v105
	s_nop 0
	v_cvt_pk_bf16_f32 v228, v104, v105
	s_waitcnt lgkmcnt(3)
	v_mfma_f32_32x32x16_bf16 v[48:63], v[212:215], v[224:227], v[48:63]
	v_exp_f32_e32 v106, v106
	ds_read_b128 v[212:215], v246 offset:13856
	v_exp_f32_e32 v107, v107
	s_nop 0
	v_cvt_pk_bf16_f32 v229, v106, v107
	s_waitcnt lgkmcnt(3)
	v_mfma_f32_32x32x16_bf16 v[32:47], v[216:219], v[224:227], v[32:47]
	v_exp_f32_e32 v108, v108
	ds_read_b128 v[216:219], v246 offset:18464
	v_exp_f32_e32 v109, v109
	s_nop 0
	v_cvt_pk_bf16_f32 v230, v108, v109
	s_waitcnt lgkmcnt(3)
	v_mfma_f32_32x32x16_bf16 v[16:31], v[220:223], v[224:227], v[16:31]
	v_exp_f32_e32 v110, v110
	ds_read_b128 v[220:223], v246 offset:23072
	v_exp_f32_e32 v111, v111
	s_nop 0
	v_cvt_pk_bf16_f32 v231, v110, v111
	s_bitcmp1_b32 s7, 0
	s_cbranch_scc0 .Lda2_nobar
	s_barrier
.Lda2_nobar:
	v_add3_u32 v247, s9, v198, v195
	ds_read_b128 v[140:143], v247 offset:0
	ds_read_b128 v[144:147], v247 offset:32
	ds_read_b128 v[148:151], v247 offset:64
	ds_read_b128 v[152:155], v247 offset:96
	s_waitcnt lgkmcnt(7)
	v_mfma_f32_32x32x16_bf16 v[0:15], v[208:211], v[228:231], v[0:15]
	v_exp_f32_e32 v80, v80
	ds_read_b128 v[208:211], v246 offset:9280
	v_exp_f32_e32 v81, v81
	v_add_f32_e32 v200, v104, v105
	v_cvt_pk_bf16_f32 v224, v80, v81
	s_waitcnt lgkmcnt(7)
	v_mfma_f32_32x32x16_bf16 v[48:63], v[212:215], v[228:231], v[48:63]
	v_exp_f32_e32 v82, v82
	ds_read_b128 v[212:215], v246 offset:13888
	v_add_f32_e32 v200, v106, v200
	v_exp_f32_e32 v83, v83
	v_add_f32_e32 v200, v107, v200
	v_cvt_pk_bf16_f32 v225, v82, v83
	s_waitcnt lgkmcnt(7)
	v_mfma_f32_32x32x16_bf16 v[32:47], v[216:219], v[228:231], v[32:47]
	v_exp_f32_e32 v84, v84
	ds_read_b128 v[216:219], v246 offset:18496
	v_add_f32_e32 v200, v108, v200
	v_exp_f32_e32 v85, v85
	v_add_f32_e32 v200, v109, v200
	v_cvt_pk_bf16_f32 v226, v84, v85
	s_waitcnt lgkmcnt(7)
	v_mfma_f32_32x32x16_bf16 v[16:31], v[220:223], v[228:231], v[16:31]
	v_exp_f32_e32 v86, v86
	ds_read_b128 v[220:223], v246 offset:23104
	v_add_f32_e32 v200, v110, v200
	v_exp_f32_e32 v87, v87
	v_add_f32_e32 v200, v111, v200
	v_cvt_pk_bf16_f32 v227, v86, v87
	s_waitcnt lgkmcnt(7)
	v_mfma_f32_32x32x16_bf16 v[96:111], v[140:143], v[112:115], v[64:79]
	v_exp_f32_e32 v88, v88
	ds_read_b128 v[140:143], v247 offset:4608
	v_exp_f32_e32 v89, v89
	s_nop 0
	v_cvt_pk_bf16_f32 v228, v88, v89
	s_waitcnt lgkmcnt(7)
	v_mfma_f32_32x32x16_bf16 v[96:111], v[144:147], v[116:119], v[96:111]
	v_exp_f32_e32 v90, v90
	ds_read_b128 v[144:147], v247 offset:4640
	v_exp_f32_e32 v91, v91
	s_nop 0
	v_cvt_pk_bf16_f32 v229, v90, v91
	s_waitcnt lgkmcnt(7)
	v_mfma_f32_32x32x16_bf16 v[96:111], v[148:151], v[120:123], v[96:111]
	v_exp_f32_e32 v92, v92
	ds_read_b128 v[148:151], v247 offset:4672
	v_exp_f32_e32 v93, v93
	s_nop 0
	v_cvt_pk_bf16_f32 v230, v92, v93
	s_waitcnt lgkmcnt(7)
	v_mfma_f32_32x32x16_bf16 v[96:111], v[152:155], v[124:127], v[96:111]
	v_exp_f32_e32 v94, v94
	ds_read_b128 v[152:155], v247 offset:4704
	v_exp_f32_e32 v95, v95
	s_nop 0
	v_cvt_pk_bf16_f32 v231, v94, v95
	s_waitcnt lgkmcnt(7)
	v_mfma_f32_32x32x16_bf16 v[0:15], v[208:211], v[224:227], v[0:15]
	v_add_f32_e32 v200, v88, v200
	ds_read_b128 v[208:211], v246 offset:9312
	v_add_f32_e32 v201, v232, v233
	v_add_f32_e32 v200, v89, v200
	v_add_f32_e32 v201, v80, v201
	v_add_f32_e32 v200, v81, v200
	s_waitcnt lgkmcnt(7)
	v_mfma_f32_32x32x16_bf16 v[48:63], v[212:215], v[224:227], v[48:63]
	v_add_f32_e32 v200, v90, v200
	ds_read_b128 v[212:215], v246 offset:13920
	v_add_f32_e32 v201, v234, v201
	v_add_f32_e32 v200, v91, v200
	v_add_f32_e32 v201, v235, v201
	v_add_f32_e32 v200, v82, v200
	v_add_f32_e32 v201, v83, v201
	s_waitcnt lgkmcnt(7)
	v_mfma_f32_32x32x16_bf16 v[32:47], v[216:219], v[224:227], v[32:47]
	v_add_f32_e32 v200, v92, v200
	ds_read_b128 v[216:219], v246 offset:18528
	v_add_f32_e32 v201, v236, v201
	v_add_f32_e32 v200, v93, v200
	v_add_f32_e32 v201, v237, v201
	v_add_f32_e32 v200, v84, v200
	v_add_f32_e32 v201, v85, v201
	s_waitcnt lgkmcnt(7)
	v_mfma_f32_32x32x16_bf16 v[16:31], v[220:223], v[224:227], v[16:31]
	v_add_f32_e32 v200, v94, v200
	ds_read_b128 v[220:223], v246 offset:23136
	v_add_f32_e32 v201, v238, v201
	v_add_f32_e32 v200, v95, v200
	v_add_f32_e32 v201, v239, v201
	v_add_f32_e32 v200, v86, v200
	v_add_f32_e32 v201, v87, v201
	v_add_f32_e32 v200, v201, v200
	v_add_f32_e32 v199, v200, v199
	s_waitcnt lgkmcnt(7)
	v_mfma_f32_32x32x16_bf16 v[80:95], v[140:143], v[112:115], v[64:79]
	s_waitcnt vmcnt(0)
	v_exp_f32_e32 v232, v96
	v_exp_f32_e32 v233, v97
	v_add3_u32 v247, s26, v193, v194
	v_cvt_pk_bf16_f32 v224, v232, v233
	ds_write_b128 v247, v[128:131] offset:0
	s_waitcnt lgkmcnt(7)
	v_mfma_f32_32x32x16_bf16 v[80:95], v[144:147], v[116:119], v[80:95]
	v_exp_f32_e32 v234, v98
	v_exp_f32_e32 v235, v99
	v_add3_u32 v247, s26, v167, v156
	v_cvt_pk_bf16_f32 v225, v234, v235
	ds_write_b128 v247, v[132:135] offset:9216
	s_waitcnt lgkmcnt(7)
	v_mfma_f32_32x32x16_bf16 v[80:95], v[148:151], v[120:123], v[80:95]
	v_exp_f32_e32 v236, v100
	v_exp_f32_e32 v237, v101
	v_add3_u32 v247, s26, v192, v156
	v_cvt_pk_bf16_f32 v226, v236, v237
	ds_write_b128 v247, v[136:139] offset:9216
	s_waitcnt lgkmcnt(7)
	v_mfma_f32_32x32x16_bf16 v[80:95], v[152:155], v[124:127], v[80:95]
	v_exp_f32_e32 v238, v102
	v_exp_f32_e32 v239, v103
	v_add3_u32 v246, s9, v197, v195
	v_cvt_pk_bf16_f32 v227, v238, v239
	s_waitcnt lgkmcnt(6)
	v_mfma_f32_32x32x16_bf16 v[0:15], v[208:211], v[228:231], v[0:15]
	ds_read_b128 v[208:211], v246 offset:9216
	s_waitcnt lgkmcnt(6)
	v_mfma_f32_32x32x16_bf16 v[48:63], v[212:215], v[228:231], v[48:63]
	ds_read_b128 v[212:215], v246 offset:13824
	s_waitcnt lgkmcnt(6)
	v_mfma_f32_32x32x16_bf16 v[32:47], v[216:219], v[228:231], v[32:47]
	ds_read_b128 v[216:219], v246 offset:18432
	s_waitcnt lgkmcnt(6)
	v_mfma_f32_32x32x16_bf16 v[16:31], v[220:223], v[228:231], v[16:31]
	ds_read_b128 v[220:223], v246 offset:23040
	v_cmp_lt_f32_e32 vcc, 0x46800000, v200
	s_add_i32 s8, s8, 0x6c00
	s_cmp_eq_u32 s8, 0x21c00
	s_cselect_b32 s8, 0, s8
	s_add_i32 s9, s9, 0x6c00
	s_cmp_eq_u32 s9, 0x21c00
	s_cselect_b32 s9, 0, s9
	s_add_i32 s26, s26, 0x6c00
	s_cmp_eq_u32 s26, 0x21c00
	s_cselect_b32 s26, 0, s26
	s_add_i32 s7, s7, 1
	s_cmpk_eq_u32 s7, 132
	s_cbranch_scc1 .Lda2_exit
	s_cbranch_vccnz .Lda2_rare_l
	s_branch .Lda2_top
